# final out-proj epilogue: row sum-of-squares and gain chunks loaded once up front (no per-chunk load+wait behind each store)
# baseline (speedup 1.0000x reference)
;     __device__ __forceinline__ void operator()(f32x4 (&acc)[2][2][4][2], const Unit& u, int wr, int wc, int fr, int fq) const {
;     ...
; #pragma unroll
;         for (int ai = 0; ai < 2; ++ai)
; #pragma unroll
;             for (int m = 0; m < 4; ++m) {
;                 const int row = u.pm * BM + ai * HALF + wr * 64 + m * 16 + fr;
;                 const float ssr = __hip_atomic_load(sumsq + row, __ATOMIC_RELAXED, __HIP_MEMORY_SCOPE_AGENT);
;                 const float r = rsqrtf(ssr * (1.0f / DM) + NORM_EPS);
; #pragma unroll
;                 for (int bj = 0; bj < 2; ++bj)
; #pragma unroll
;                     for (int n = 0; n < 2; ++n) {
;                         const int c = col0 + bj * HALF + n * 4;
;                         const f32x4 g = *(const f32x4*)(fg + c);
;                         *(f32x4*)(out + (size_t)row * DM + c) = acc[ai][bj][m][n] * r * g;
;                     }
;             }
.LBB0_744:
	s_or_b64 exec, exec, s[0:1]
	s_barrier
	s_nop 0
	v_lshl_add_u64 v[144:145], v[144:145], 2, s[50:51]
	global_load_dword v240, v[148:149], off sc1
	global_load_dword v241, v[154:155], off sc1
	global_load_dword v242, v[158:159], off sc1
	global_load_dword v243, v[162:163], off sc1
	global_load_dword v244, v[166:167], off sc1
	global_load_dword v245, v[170:171], off sc1
	global_load_dword v246, v[172:173], off sc1
	global_load_dword v247, v[174:175], off sc1
	global_load_dwordx4 v[224:227], v[144:145], off
	global_load_dwordx4 v[228:231], v[144:145], off offset:16
	global_load_dwordx4 v[232:235], v[144:145], off offset:512
	global_load_dwordx4 v[236:239], v[144:145], off offset:528
	s_waitcnt vmcnt(0)
	v_mov_b32_e32 v148, v240
	s_nop 1
	v_mov_b32_e32 v190, v224
	v_mov_b32_e32 v191, v225
	v_mov_b32_e32 v192, v226
	v_mov_b32_e32 v193, v227
	s_mov_b64 s[0:1], -1
	s_nop 0
	v_fmamk_f32 v148, v148, 0x3a800000, v202
	v_mul_f32_e32 v149, 0x4b800000, v148
	v_cmp_gt_f32_e32 vcc, s18, v148
	s_nop 1
	v_cndmask_b32_e32 v148, v148, v149, vcc
	v_rsq_f32_e32 v148, v148
	s_nop 0
	v_mul_f32_e32 v149, 0x45800000, v148
	v_cndmask_b32_e32 v148, v148, v149, vcc
	v_pk_mul_f32 v[128:129], v[128:129], v[148:149] op_sel_hi:[1,0]
	v_pk_mul_f32 v[130:131], v[130:131], v[148:149] op_sel_hi:[1,0]
	s_nop 0
	v_pk_mul_f32 v[128:129], v[190:191], v[128:129]
	v_pk_mul_f32 v[130:131], v[192:193], v[130:131]
	global_store_dwordx4 v[142:143], v[128:131], off
	s_nop 1
	v_mov_b32_e32 v128, v228
	v_mov_b32_e32 v129, v229
	v_mov_b32_e32 v130, v230
	v_mov_b32_e32 v131, v231
	v_pk_mul_f32 v[126:127], v[126:127], v[148:149] op_sel_hi:[1,0]
	v_pk_mul_f32 v[124:125], v[124:125], v[148:149] op_sel_hi:[1,0]
	v_pk_mul_f32 v[122:123], v[122:123], v[148:149] op_sel_hi:[1,0]
	v_pk_mul_f32 v[120:121], v[120:121], v[148:149] op_sel_hi:[1,0]
	v_pk_mul_f32 v[118:119], v[118:119], v[148:149] op_sel_hi:[1,0]
	v_pk_mul_f32 v[116:117], v[116:117], v[148:149] op_sel_hi:[1,0]
	s_nop 0
	v_pk_mul_f32 v[124:125], v[128:129], v[124:125]
	v_pk_mul_f32 v[126:127], v[130:131], v[126:127]
	global_store_dwordx4 v[142:143], v[124:127], off offset:16
	s_nop 1
	v_mov_b32_e32 v124, v232
	v_mov_b32_e32 v125, v233
	v_mov_b32_e32 v126, v234
	v_mov_b32_e32 v127, v235
	s_nop 0
	v_pk_mul_f32 v[120:121], v[124:125], v[120:121]
	v_pk_mul_f32 v[122:123], v[126:127], v[122:123]
	global_store_dwordx4 v[142:143], v[120:123], off offset:512
	s_nop 1
	v_mov_b32_e32 v120, v236
	v_mov_b32_e32 v121, v237
	v_mov_b32_e32 v122, v238
	v_mov_b32_e32 v123, v239
	s_nop 0
	v_pk_mul_f32 v[116:117], v[120:121], v[116:117]
	v_pk_mul_f32 v[118:119], v[122:123], v[118:119]
	global_store_dwordx4 v[142:143], v[116:119], off offset:528
	s_nop 1
	v_mov_b32_e32 v120, v241
	s_nop 0
	s_nop 1
	v_mov_b32_e32 v116, v224
	v_mov_b32_e32 v117, v225
	v_mov_b32_e32 v118, v226
	v_mov_b32_e32 v119, v227
	s_nop 0
	v_fmamk_f32 v120, v120, 0x3a800000, v202
	v_mul_f32_e32 v121, 0x4b800000, v120
	v_cmp_gt_f32_e32 vcc, s18, v120
	s_nop 1
	v_cndmask_b32_e32 v120, v120, v121, vcc
	v_rsq_f32_e32 v120, v120
	s_nop 0
	v_mul_f32_e32 v121, 0x45800000, v120
	v_cndmask_b32_e32 v120, v120, v121, vcc
	v_pk_mul_f32 v[110:111], v[110:111], v[120:121] op_sel_hi:[1,0]
	v_pk_mul_f32 v[112:113], v[112:113], v[120:121] op_sel_hi:[1,0]
	s_nop 0
	v_pk_mul_f32 v[110:111], v[116:117], v[110:111]
	v_pk_mul_f32 v[112:113], v[118:119], v[112:113]
	global_store_dwordx4 v[146:147], v[110:113], off
	s_nop 1
	v_mov_b32_e32 v110, v228
	v_mov_b32_e32 v111, v229
	v_mov_b32_e32 v112, v230
	v_mov_b32_e32 v113, v231
	v_pk_mul_f32 v[108:109], v[108:109], v[120:121] op_sel_hi:[1,0]
	v_pk_mul_f32 v[106:107], v[106:107], v[120:121] op_sel_hi:[1,0]
	v_pk_mul_f32 v[104:105], v[104:105], v[120:121] op_sel_hi:[1,0]
	v_pk_mul_f32 v[102:103], v[102:103], v[120:121] op_sel_hi:[1,0]
	v_pk_mul_f32 v[100:101], v[100:101], v[120:121] op_sel_hi:[1,0]
	v_pk_mul_f32 v[98:99], v[98:99], v[120:121] op_sel_hi:[1,0]
	s_nop 0
	v_pk_mul_f32 v[106:107], v[110:111], v[106:107]
	v_pk_mul_f32 v[108:109], v[112:113], v[108:109]
	global_store_dwordx4 v[146:147], v[106:109], off offset:16
	s_nop 1
	v_mov_b32_e32 v106, v232
	v_mov_b32_e32 v107, v233
	v_mov_b32_e32 v108, v234
	v_mov_b32_e32 v109, v235
	s_nop 0
	v_pk_mul_f32 v[102:103], v[106:107], v[102:103]
	v_pk_mul_f32 v[104:105], v[108:109], v[104:105]
	global_store_dwordx4 v[146:147], v[102:105], off offset:512
	s_nop 1
	v_mov_b32_e32 v102, v236
	v_mov_b32_e32 v103, v237
	v_mov_b32_e32 v104, v238
	v_mov_b32_e32 v105, v239
	s_nop 0
	v_pk_mul_f32 v[98:99], v[102:103], v[98:99]
	v_pk_mul_f32 v[100:101], v[104:105], v[100:101]
	global_store_dwordx4 v[146:147], v[98:101], off offset:528
	s_nop 1
	v_mov_b32_e32 v102, v242
	s_nop 0
	s_nop 1
	v_mov_b32_e32 v98, v224
	v_mov_b32_e32 v99, v225
	v_mov_b32_e32 v100, v226
	v_mov_b32_e32 v101, v227
	s_nop 0
	v_fmamk_f32 v102, v102, 0x3a800000, v202
	v_mul_f32_e32 v103, 0x4b800000, v102
	v_cmp_gt_f32_e32 vcc, s18, v102
	s_nop 1
	v_cndmask_b32_e32 v102, v102, v103, vcc
	v_rsq_f32_e32 v102, v102
	s_nop 0
	v_mul_f32_e32 v103, 0x45800000, v102
	v_cndmask_b32_e32 v102, v102, v103, vcc
	v_pk_mul_f32 v[94:95], v[94:95], v[102:103] op_sel_hi:[1,0]
	v_pk_mul_f32 v[96:97], v[96:97], v[102:103] op_sel_hi:[1,0]
	s_nop 0
	v_pk_mul_f32 v[94:95], v[98:99], v[94:95]
	v_pk_mul_f32 v[96:97], v[100:101], v[96:97]
	global_store_dwordx4 v[150:151], v[94:97], off
	s_nop 1
	v_mov_b32_e32 v94, v228
	v_mov_b32_e32 v95, v229
	v_mov_b32_e32 v96, v230
	v_mov_b32_e32 v97, v231
	v_pk_mul_f32 v[92:93], v[92:93], v[102:103] op_sel_hi:[1,0]
	v_pk_mul_f32 v[90:91], v[90:91], v[102:103] op_sel_hi:[1,0]
	v_pk_mul_f32 v[88:89], v[88:89], v[102:103] op_sel_hi:[1,0]
;     __device__ __forceinline__ void operator()(f32x4 (&acc)[2][2][4][2], const Unit& u, int wr, int wc, int fr, int fq) const {
;     ...
; #pragma unroll
;         for (int ai = 0; ai < 2; ++ai)
; #pragma unroll
;             for (int m = 0; m < 4; ++m) {
;                 const int row = u.pm * BM + ai * HALF + wr * 64 + m * 16 + fr;
;                 const float ssr = __hip_atomic_load(sumsq + row, __ATOMIC_RELAXED, __HIP_MEMORY_SCOPE_AGENT);
;                 const float r = rsqrtf(ssr * (1.0f / DM) + NORM_EPS);
; #pragma unroll
;                 for (int bj = 0; bj < 2; ++bj)
; #pragma unroll
;                     for (int n = 0; n < 2; ++n) {
;                         const int c = col0 + bj * HALF + n * 4;
;                         const f32x4 g = *(const f32x4*)(fg + c);
;                         *(f32x4*)(out + (size_t)row * DM + c) = acc[ai][bj][m][n] * r * g;
;                     }
;             }
	v_pk_mul_f32 v[86:87], v[86:87], v[102:103] op_sel_hi:[1,0]
	v_pk_mul_f32 v[84:85], v[84:85], v[102:103] op_sel_hi:[1,0]
	v_pk_mul_f32 v[82:83], v[82:83], v[102:103] op_sel_hi:[1,0]
	s_nop 0
	v_pk_mul_f32 v[90:91], v[94:95], v[90:91]
	v_pk_mul_f32 v[92:93], v[96:97], v[92:93]
	global_store_dwordx4 v[150:151], v[90:93], off offset:16
	s_nop 1
	v_mov_b32_e32 v90, v232
	v_mov_b32_e32 v91, v233
	v_mov_b32_e32 v92, v234
	v_mov_b32_e32 v93, v235
	s_nop 0
	v_pk_mul_f32 v[86:87], v[90:91], v[86:87]
	v_pk_mul_f32 v[88:89], v[92:93], v[88:89]
	global_store_dwordx4 v[150:151], v[86:89], off offset:512
	s_nop 1
	v_mov_b32_e32 v86, v236
	v_mov_b32_e32 v87, v237
	v_mov_b32_e32 v88, v238
	v_mov_b32_e32 v89, v239
	s_nop 0
	v_pk_mul_f32 v[82:83], v[86:87], v[82:83]
	v_pk_mul_f32 v[84:85], v[88:89], v[84:85]
	global_store_dwordx4 v[150:151], v[82:85], off offset:528
	s_nop 1
	v_mov_b32_e32 v86, v243
	s_nop 0
	s_nop 1
	v_mov_b32_e32 v82, v224
	v_mov_b32_e32 v83, v225
	v_mov_b32_e32 v84, v226
	v_mov_b32_e32 v85, v227
	s_nop 0
	v_fmamk_f32 v86, v86, 0x3a800000, v202
	v_mul_f32_e32 v87, 0x4b800000, v86
	v_cmp_gt_f32_e32 vcc, s18, v86
	s_nop 1
	v_cndmask_b32_e32 v86, v86, v87, vcc
	v_rsq_f32_e32 v86, v86
	s_nop 0
	v_mul_f32_e32 v87, 0x45800000, v86
	v_cndmask_b32_e32 v86, v86, v87, vcc
	v_pk_mul_f32 v[78:79], v[78:79], v[86:87] op_sel_hi:[1,0]
	v_pk_mul_f32 v[80:81], v[80:81], v[86:87] op_sel_hi:[1,0]
	s_nop 0
	v_pk_mul_f32 v[78:79], v[82:83], v[78:79]
	v_pk_mul_f32 v[80:81], v[84:85], v[80:81]
	global_store_dwordx4 v[156:157], v[78:81], off
	s_nop 1
	v_mov_b32_e32 v78, v228
	v_mov_b32_e32 v79, v229
	v_mov_b32_e32 v80, v230
	v_mov_b32_e32 v81, v231
	v_pk_mul_f32 v[76:77], v[76:77], v[86:87] op_sel_hi:[1,0]
	v_pk_mul_f32 v[74:75], v[74:75], v[86:87] op_sel_hi:[1,0]
	v_pk_mul_f32 v[72:73], v[72:73], v[86:87] op_sel_hi:[1,0]
	v_pk_mul_f32 v[70:71], v[70:71], v[86:87] op_sel_hi:[1,0]
	v_pk_mul_f32 v[68:69], v[68:69], v[86:87] op_sel_hi:[1,0]
	v_pk_mul_f32 v[66:67], v[66:67], v[86:87] op_sel_hi:[1,0]
	s_nop 0
	v_pk_mul_f32 v[74:75], v[78:79], v[74:75]
	v_pk_mul_f32 v[76:77], v[80:81], v[76:77]
	global_store_dwordx4 v[156:157], v[74:77], off offset:16
	s_nop 1
	v_mov_b32_e32 v74, v232
	v_mov_b32_e32 v75, v233
	v_mov_b32_e32 v76, v234
	v_mov_b32_e32 v77, v235
	s_nop 0
	v_pk_mul_f32 v[70:71], v[74:75], v[70:71]
	v_pk_mul_f32 v[72:73], v[76:77], v[72:73]
	global_store_dwordx4 v[156:157], v[70:73], off offset:512
	s_nop 1
	v_mov_b32_e32 v70, v236
	v_mov_b32_e32 v71, v237
	v_mov_b32_e32 v72, v238
	v_mov_b32_e32 v73, v239
	s_nop 0
	v_pk_mul_f32 v[66:67], v[70:71], v[66:67]
	v_pk_mul_f32 v[68:69], v[72:73], v[68:69]
	global_store_dwordx4 v[156:157], v[66:69], off offset:528
	s_nop 1
	v_mov_b32_e32 v70, v244
	s_nop 0
	s_nop 1
	v_mov_b32_e32 v66, v224
	v_mov_b32_e32 v67, v225
	v_mov_b32_e32 v68, v226
	v_mov_b32_e32 v69, v227
	s_nop 0
	v_fmamk_f32 v70, v70, 0x3a800000, v202
	v_mul_f32_e32 v71, 0x4b800000, v70
	v_cmp_gt_f32_e32 vcc, s18, v70
	s_nop 1
	v_cndmask_b32_e32 v70, v70, v71, vcc
	v_rsq_f32_e32 v70, v70
	s_nop 0
	v_mul_f32_e32 v71, 0x45800000, v70
	v_cndmask_b32_e32 v70, v70, v71, vcc
	v_pk_mul_f32 v[62:63], v[62:63], v[70:71] op_sel_hi:[1,0]
	v_pk_mul_f32 v[64:65], v[64:65], v[70:71] op_sel_hi:[1,0]
	s_nop 0
	v_pk_mul_f32 v[62:63], v[66:67], v[62:63]
	v_pk_mul_f32 v[64:65], v[68:69], v[64:65]
	global_store_dwordx4 v[160:161], v[62:65], off
	s_nop 1
	v_mov_b32_e32 v62, v228
	v_mov_b32_e32 v63, v229
	v_mov_b32_e32 v64, v230
	v_mov_b32_e32 v65, v231
	v_pk_mul_f32 v[60:61], v[60:61], v[70:71] op_sel_hi:[1,0]
	v_pk_mul_f32 v[58:59], v[58:59], v[70:71] op_sel_hi:[1,0]
	v_pk_mul_f32 v[56:57], v[56:57], v[70:71] op_sel_hi:[1,0]
	v_pk_mul_f32 v[54:55], v[54:55], v[70:71] op_sel_hi:[1,0]
	v_pk_mul_f32 v[52:53], v[52:53], v[70:71] op_sel_hi:[1,0]
	v_pk_mul_f32 v[50:51], v[50:51], v[70:71] op_sel_hi:[1,0]
	s_nop 0
	v_pk_mul_f32 v[58:59], v[62:63], v[58:59]
	v_pk_mul_f32 v[60:61], v[64:65], v[60:61]
	global_store_dwordx4 v[160:161], v[58:61], off offset:16
	s_nop 1
	v_mov_b32_e32 v58, v232
	v_mov_b32_e32 v59, v233
	v_mov_b32_e32 v60, v234
	v_mov_b32_e32 v61, v235
	s_nop 0
	v_pk_mul_f32 v[54:55], v[58:59], v[54:55]
	v_pk_mul_f32 v[56:57], v[60:61], v[56:57]
	global_store_dwordx4 v[160:161], v[54:57], off offset:512
	s_nop 1
	v_mov_b32_e32 v54, v236
	v_mov_b32_e32 v55, v237
	v_mov_b32_e32 v56, v238
	v_mov_b32_e32 v57, v239
	s_nop 0
	v_pk_mul_f32 v[50:51], v[54:55], v[50:51]
	v_pk_mul_f32 v[52:53], v[56:57], v[52:53]
	global_store_dwordx4 v[160:161], v[50:53], off offset:528
	s_nop 1
	v_mov_b32_e32 v54, v245
	s_nop 0
	s_nop 1
	v_mov_b32_e32 v50, v224
	v_mov_b32_e32 v51, v225
	v_mov_b32_e32 v52, v226
	v_mov_b32_e32 v53, v227
	s_nop 0
	v_fmamk_f32 v54, v54, 0x3a800000, v202
	v_mul_f32_e32 v55, 0x4b800000, v54
	v_cmp_gt_f32_e32 vcc, s18, v54
	s_nop 1
	v_cndmask_b32_e32 v54, v54, v55, vcc
	v_rsq_f32_e32 v54, v54
	s_nop 0
	v_mul_f32_e32 v55, 0x45800000, v54
	v_cndmask_b32_e32 v54, v54, v55, vcc
	v_pk_mul_f32 v[46:47], v[46:47], v[54:55] op_sel_hi:[1,0]
	v_pk_mul_f32 v[48:49], v[48:49], v[54:55] op_sel_hi:[1,0]
; #define PG8_BAR __builtin_amdgcn_s_barrier()
;     __device__ __forceinline__ void operator()(f32x4 (&acc)[2][2][4][2], const Unit& u, int wr, int wc, int fr, int fq) const {
;     ...
; #pragma unroll
;         for (int ai = 0; ai < 2; ++ai)
; #pragma unroll
;             for (int m = 0; m < 4; ++m) {
;                 const int row = u.pm * BM + ai * HALF + wr * 64 + m * 16 + fr;
;                 const float ssr = __hip_atomic_load(sumsq + row, __ATOMIC_RELAXED, __HIP_MEMORY_SCOPE_AGENT);
;                 const float r = rsqrtf(ssr * (1.0f / DM) + NORM_EPS);
; #pragma unroll
;                 for (int bj = 0; bj < 2; ++bj)
; #pragma unroll
;                     for (int n = 0; n < 2; ++n) {
;                         const int c = col0 + bj * HALF + n * 4;
;                         const f32x4 g = *(const f32x4*)(fg + c);
;                         *(f32x4*)(out + (size_t)row * DM + c) = acc[ai][bj][m][n] * r * g;
;                     }
;             }
; template <class Epi, class Sched, bool ALIGN_EPI = false, bool SP2 = false>
; __device__ __forceinline__ void gemm_phase(PG8_LAS unsigned char* lds, const Gemm g, const Sched& S, const Epi& E) {
;     ...
;         if (!has_next) break;
; #pragma unroll
;         for (int a = 0; a < 2; ++a)
; #pragma unroll
;             for (int b = 0; b < 2; ++b)
; #pragma unroll
;                 for (int m = 0; m < 4; ++m)
; #pragma unroll
;                     for (int n = 0; n < 2; ++n) acc[a][b][m][n] = (f32x4){0.f, 0.f, 0.f, 0.f};
;         cur = nxt; cA = nA; cB = nB; ++ui;
;         if constexpr (ALIGN_EPI) { if (wr == 1) PG8_BAR; }
	s_nop 0
	v_pk_mul_f32 v[46:47], v[50:51], v[46:47]
	v_pk_mul_f32 v[48:49], v[52:53], v[48:49]
	global_store_dwordx4 v[164:165], v[46:49], off
	s_nop 1
	v_mov_b32_e32 v46, v228
	v_mov_b32_e32 v47, v229
	v_mov_b32_e32 v48, v230
	v_mov_b32_e32 v49, v231
	v_pk_mul_f32 v[44:45], v[44:45], v[54:55] op_sel_hi:[1,0]
	v_pk_mul_f32 v[42:43], v[42:43], v[54:55] op_sel_hi:[1,0]
	v_pk_mul_f32 v[40:41], v[40:41], v[54:55] op_sel_hi:[1,0]
	v_pk_mul_f32 v[38:39], v[38:39], v[54:55] op_sel_hi:[1,0]
	v_pk_mul_f32 v[36:37], v[36:37], v[54:55] op_sel_hi:[1,0]
	v_pk_mul_f32 v[34:35], v[34:35], v[54:55] op_sel_hi:[1,0]
	s_nop 0
	v_pk_mul_f32 v[42:43], v[46:47], v[42:43]
	v_pk_mul_f32 v[44:45], v[48:49], v[44:45]
	global_store_dwordx4 v[164:165], v[42:45], off offset:16
	s_nop 1
	v_mov_b32_e32 v42, v232
	v_mov_b32_e32 v43, v233
	v_mov_b32_e32 v44, v234
	v_mov_b32_e32 v45, v235
	s_nop 0
	v_pk_mul_f32 v[38:39], v[42:43], v[38:39]
	v_pk_mul_f32 v[40:41], v[44:45], v[40:41]
	global_store_dwordx4 v[164:165], v[38:41], off offset:512
	s_nop 1
	v_mov_b32_e32 v38, v236
	v_mov_b32_e32 v39, v237
	v_mov_b32_e32 v40, v238
	v_mov_b32_e32 v41, v239
	s_nop 0
	v_pk_mul_f32 v[34:35], v[38:39], v[34:35]
	v_pk_mul_f32 v[36:37], v[40:41], v[36:37]
	global_store_dwordx4 v[164:165], v[34:37], off offset:528
	s_nop 1
	v_mov_b32_e32 v38, v246
	s_nop 0
	s_nop 1
	v_mov_b32_e32 v34, v224
	v_mov_b32_e32 v35, v225
	v_mov_b32_e32 v36, v226
	v_mov_b32_e32 v37, v227
	s_nop 0
	v_fmamk_f32 v38, v38, 0x3a800000, v202
	v_mul_f32_e32 v39, 0x4b800000, v38
	v_cmp_gt_f32_e32 vcc, s18, v38
	s_nop 1
	v_cndmask_b32_e32 v38, v38, v39, vcc
	v_rsq_f32_e32 v38, v38
	s_nop 0
	v_mul_f32_e32 v39, 0x45800000, v38
	v_cndmask_b32_e32 v38, v38, v39, vcc
	v_pk_mul_f32 v[30:31], v[30:31], v[38:39] op_sel_hi:[1,0]
	v_pk_mul_f32 v[32:33], v[32:33], v[38:39] op_sel_hi:[1,0]
	s_nop 0
	v_pk_mul_f32 v[30:31], v[34:35], v[30:31]
	v_pk_mul_f32 v[32:33], v[36:37], v[32:33]
	global_store_dwordx4 v[168:169], v[30:33], off
	s_nop 1
	v_mov_b32_e32 v30, v228
	v_mov_b32_e32 v31, v229
	v_mov_b32_e32 v32, v230
	v_mov_b32_e32 v33, v231
	v_pk_mul_f32 v[28:29], v[28:29], v[38:39] op_sel_hi:[1,0]
	v_pk_mul_f32 v[26:27], v[26:27], v[38:39] op_sel_hi:[1,0]
	v_pk_mul_f32 v[24:25], v[24:25], v[38:39] op_sel_hi:[1,0]
	v_pk_mul_f32 v[22:23], v[22:23], v[38:39] op_sel_hi:[1,0]
	v_pk_mul_f32 v[20:21], v[20:21], v[38:39] op_sel_hi:[1,0]
	v_pk_mul_f32 v[18:19], v[18:19], v[38:39] op_sel_hi:[1,0]
	s_nop 0
	v_pk_mul_f32 v[26:27], v[30:31], v[26:27]
	v_pk_mul_f32 v[28:29], v[32:33], v[28:29]
	global_store_dwordx4 v[168:169], v[26:29], off offset:16
	s_nop 1
	v_mov_b32_e32 v26, v232
	v_mov_b32_e32 v27, v233
	v_mov_b32_e32 v28, v234
	v_mov_b32_e32 v29, v235
	s_nop 0
	v_pk_mul_f32 v[22:23], v[26:27], v[22:23]
	v_pk_mul_f32 v[24:25], v[28:29], v[24:25]
	global_store_dwordx4 v[168:169], v[22:25], off offset:512
	s_nop 1
	v_mov_b32_e32 v22, v236
	v_mov_b32_e32 v23, v237
	v_mov_b32_e32 v24, v238
	v_mov_b32_e32 v25, v239
	s_nop 0
	v_pk_mul_f32 v[18:19], v[22:23], v[18:19]
	v_pk_mul_f32 v[20:21], v[24:25], v[20:21]
	global_store_dwordx4 v[168:169], v[18:21], off offset:528
	s_nop 1
	v_mov_b32_e32 v22, v247
	s_nop 0
	s_nop 1
	v_mov_b32_e32 v18, v224
	v_mov_b32_e32 v19, v225
	v_mov_b32_e32 v20, v226
	v_mov_b32_e32 v21, v227
	s_nop 0
	v_fmamk_f32 v22, v22, 0x3a800000, v202
	v_mul_f32_e32 v23, 0x4b800000, v22
	v_cmp_gt_f32_e32 vcc, s18, v22
	s_nop 1
	v_cndmask_b32_e32 v22, v22, v23, vcc
	v_rsq_f32_e32 v22, v22
	s_nop 0
	v_mul_f32_e32 v23, 0x45800000, v22
	v_cndmask_b32_e32 v22, v22, v23, vcc
	v_pk_mul_f32 v[14:15], v[14:15], v[22:23] op_sel_hi:[1,0]
	v_pk_mul_f32 v[16:17], v[16:17], v[22:23] op_sel_hi:[1,0]
	s_nop 0
	v_pk_mul_f32 v[14:15], v[18:19], v[14:15]
	v_pk_mul_f32 v[16:17], v[20:21], v[16:17]
	global_store_dwordx4 v[152:153], v[14:17], off
	s_nop 1
	v_mov_b32_e32 v14, v228
	v_mov_b32_e32 v15, v229
	v_mov_b32_e32 v16, v230
	v_mov_b32_e32 v17, v231
	v_pk_mul_f32 v[12:13], v[12:13], v[22:23] op_sel_hi:[1,0]
	v_pk_mul_f32 v[10:11], v[10:11], v[22:23] op_sel_hi:[1,0]
	v_pk_mul_f32 v[8:9], v[8:9], v[22:23] op_sel_hi:[1,0]
	v_pk_mul_f32 v[6:7], v[6:7], v[22:23] op_sel_hi:[1,0]
	v_pk_mul_f32 v[4:5], v[4:5], v[22:23] op_sel_hi:[1,0]
	v_pk_mul_f32 v[2:3], v[2:3], v[22:23] op_sel_hi:[1,0]
	s_andn2_b64 vcc, exec, s[42:43]
	s_nop 0
	v_pk_mul_f32 v[10:11], v[14:15], v[10:11]
	v_pk_mul_f32 v[12:13], v[16:17], v[12:13]
	global_store_dwordx4 v[152:153], v[10:13], off offset:16
	s_nop 1
	v_mov_b32_e32 v10, v232
	v_mov_b32_e32 v11, v233
	v_mov_b32_e32 v12, v234
	v_mov_b32_e32 v13, v235
	s_nop 0
	v_pk_mul_f32 v[6:7], v[10:11], v[6:7]
	v_pk_mul_f32 v[8:9], v[12:13], v[8:9]
	global_store_dwordx4 v[152:153], v[6:9], off offset:512
	s_nop 1
	v_mov_b32_e32 v6, v236
	v_mov_b32_e32 v7, v237
	v_mov_b32_e32 v8, v238
	v_mov_b32_e32 v9, v239
	s_nop 0
	v_pk_mul_f32 v[2:3], v[6:7], v[2:3]
	v_pk_mul_f32 v[4:5], v[8:9], v[4:5]
	global_store_dwordx4 v[152:153], v[2:5], off offset:528
	s_cbranch_vccnz .LBB0_703
	s_andn2_b64 vcc, exec, s[20:21]
	s_cbranch_vccnz .LBB0_702
	s_barrier
	s_branch .LBB0_702
